# diff-attn unit epilogue: the 16 sub-LN gain loads issued together with counted waits instead of load-wait-store serial chain
# speedup vs baseline: 1.0058x; 1.0058x over previous
; __device__ __forceinline__ float xhalf_sum(float v) { auto rr = __builtin_amdgcn_permlane32_swap(__float_as_uint(v), __float_as_uint(v), false, false); return __uint_as_float(rr[0]) + __uint_as_float(rr[1]); }
; template <int MODE, bool FROZEN = false>
; __device__ __forceinline__ bool attn_unit(LAS unsigned char* lds, const Params& p, int l, int ua, int ub) {
;     ...
;         if (wid < 4) {
;             float ss = 0.f;
; #pragma unroll
;             for (int nb = 0; nb < NB; ++nb)
; #pragma unroll
;                 for (int r = 0; r < 16; ++r) { const float a = o[nb][r] - lam * ex[(wid * 64 + nb * 16 + r) * 64 + lane]; o[nb][r] = a; ss += a * a; }
;             ss = xhalf_sum(ss);
;             const float rinv = (1.0f - lam_init) / sqrtf(ss * (1.0f / 128.0f) + 1e-6f);
;             const float* sg = p.diff_subln_g + (size_t)l * 128;
.LBB0_132:
	s_cmp_gt_i32 s56, 3
	s_waitcnt lgkmcnt(0)
	s_barrier
	s_cbranch_scc1 .LBB0_92
	s_lshl_b32 s0, s54, 8
	s_and_b32 s0, s0, 0xffffc000
	v_sub_f32_e32 v2, v167, v168
	s_add_i32 s0, s0, 0
	v_add_f32_e32 v52, v162, v2
	v_lshl_add_u32 v2, v164, 2, s0
	ds_read2st64_b32 v[54:55], v2 offset1:1
	ds_read2st64_b32 v[56:57], v2 offset0:2 offset1:3
	ds_read2st64_b32 v[58:59], v2 offset0:4 offset1:5
	ds_read2st64_b32 v[60:61], v2 offset0:6 offset1:7
	ds_read2st64_b32 v[62:63], v2 offset0:8 offset1:9
	ds_read2st64_b32 v[70:71], v2 offset0:10 offset1:11
	ds_read2st64_b32 v[72:73], v2 offset0:12 offset1:13
	ds_read2st64_b32 v[118:119], v2 offset0:14 offset1:15
	ds_read2st64_b32 v[120:121], v2 offset0:16 offset1:17
	ds_read2st64_b32 v[122:123], v2 offset0:18 offset1:19
	ds_read2st64_b32 v[124:125], v2 offset0:20 offset1:21
	ds_read2st64_b32 v[126:127], v2 offset0:22 offset1:23
	ds_read2st64_b32 v[128:129], v2 offset0:24 offset1:25
	ds_read2st64_b32 v[130:131], v2 offset0:26 offset1:27
	ds_read2st64_b32 v[132:133], v2 offset0:28 offset1:29
	ds_read2st64_b32 v[134:135], v2 offset0:30 offset1:31
	ds_read2st64_b32 v[136:137], v2 offset0:32 offset1:33
	ds_read2st64_b32 v[138:139], v2 offset0:34 offset1:35
	ds_read2st64_b32 v[140:141], v2 offset0:36 offset1:37
	ds_read2st64_b32 v[142:143], v2 offset0:38 offset1:39
	ds_read2st64_b32 v[116:117], v2 offset0:40 offset1:41
	s_waitcnt vmcnt(0)
	ds_read2st64_b32 v[144:145], v2 offset0:42 offset1:43
	ds_read2st64_b32 v[96:97], v2 offset0:44 offset1:45
	ds_read2st64_b32 v[98:99], v2 offset0:46 offset1:47
	ds_read2st64_b32 v[92:93], v2 offset0:48 offset1:49
	ds_read2st64_b32 v[94:95], v2 offset0:50 offset1:51
	ds_read2st64_b32 v[80:81], v2 offset0:52 offset1:53
	ds_read2st64_b32 v[82:83], v2 offset0:54 offset1:55
	ds_read2st64_b32 v[74:75], v2 offset0:56 offset1:57
	ds_read2st64_b32 v[78:79], v2 offset0:58 offset1:59
	ds_read2st64_b32 v[66:67], v2 offset0:60 offset1:61
	ds_read2st64_b32 v[2:3], v2 offset0:62 offset1:63
	s_waitcnt lgkmcnt(14)
	v_pk_fma_f32 v[68:69], v[52:53], v[54:55], v[6:7] op_sel_hi:[0,1,1] neg_lo:[1,0,0] neg_hi:[1,0,0]
	v_mul_f32_e32 v6, v69, v69
	v_readlane_b32 s0, v252, 25
	v_pk_fma_f32 v[64:65], v[52:53], v[56:57], v[114:115] op_sel_hi:[0,1,1] neg_lo:[1,0,0] neg_hi:[1,0,0]
	v_pk_fma_f32 v[6:7], v[68:69], v[68:69], v[6:7] op_sel_hi:[1,1,0]
	s_waitcnt lgkmcnt(0)
	v_pk_fma_f32 v[4:5], v[52:53], v[2:3], v[0:1] op_sel_hi:[0,1,1] neg_lo:[1,0,0] neg_hi:[1,0,0]
	v_lshlrev_b64 v[0:1], 10, v[150:151]
	v_readlane_b32 s1, v252, 26
	v_pk_fma_f32 v[6:7], v[64:65], v[64:65], v[6:7]
	v_mul_f32_e32 v54, v65, v65
	v_lshl_add_u64 v[0:1], s[0:1], 0, v[0:1]
	s_lshl_b32 s8, s55, 1
	v_pk_add_f32 v[54:55], v[6:7], v[54:55] op_sel_hi:[1,0]
	v_pk_fma_f32 v[88:89], v[52:53], v[58:59], v[110:111] op_sel_hi:[0,1,1] neg_lo:[1,0,0] neg_hi:[1,0,0]
	v_lshl_add_u64 v[76:77], v[0:1], 0, s[8:9]
	v_lshlrev_b32_e32 v196, 3, v149
	v_pk_fma_f32 v[54:55], v[88:89], v[88:89], v[54:55]
	v_mul_f32_e32 v56, v89, v89
	v_lshl_add_u64 v[6:7], v[76:77], 0, v[196:197]
	v_pk_fma_f32 v[76:77], v[52:53], v[60:61], v[112:113] op_sel_hi:[0,1,1] neg_lo:[1,0,0] neg_hi:[1,0,0]
	v_pk_add_f32 v[54:55], v[54:55], v[56:57] op_sel_hi:[1,0]
	v_mul_f32_e32 v56, v77, v77
	v_pk_fma_f32 v[54:55], v[76:77], v[76:77], v[54:55]
	v_pk_fma_f32 v[90:91], v[52:53], v[62:63], v[106:107] op_sel_hi:[0,1,1] neg_lo:[1,0,0] neg_hi:[1,0,0]
	v_pk_add_f32 v[54:55], v[54:55], v[56:57] op_sel_hi:[1,0]
	v_mul_f32_e32 v56, v91, v91
	v_pk_fma_f32 v[54:55], v[90:91], v[90:91], v[54:55]
	v_pk_fma_f32 v[70:71], v[52:53], v[70:71], v[108:109] op_sel_hi:[0,1,1] neg_lo:[1,0,0] neg_hi:[1,0,0]
	v_pk_add_f32 v[54:55], v[54:55], v[56:57] op_sel_hi:[1,0]
	v_mul_f32_e32 v56, v71, v71
	v_pk_fma_f32 v[54:55], v[70:71], v[70:71], v[54:55]
	v_pk_fma_f32 v[72:73], v[52:53], v[72:73], v[102:103] op_sel_hi:[0,1,1] neg_lo:[1,0,0] neg_hi:[1,0,0]
	v_pk_add_f32 v[54:55], v[54:55], v[56:57] op_sel_hi:[1,0]
	v_mul_f32_e32 v56, v73, v73
	v_pk_fma_f32 v[54:55], v[72:73], v[72:73], v[54:55]
	v_pk_fma_f32 v[60:61], v[52:53], v[118:119], v[104:105] op_sel_hi:[0,1,1] neg_lo:[1,0,0] neg_hi:[1,0,0]
	v_pk_add_f32 v[54:55], v[54:55], v[56:57] op_sel_hi:[1,0]
	v_mul_f32_e32 v56, v61, v61
	v_pk_fma_f32 v[54:55], v[60:61], v[60:61], v[54:55]
	v_pk_fma_f32 v[62:63], v[52:53], v[120:121], v[100:101] op_sel_hi:[0,1,1] neg_lo:[1,0,0] neg_hi:[1,0,0]
	v_pk_add_f32 v[54:55], v[54:55], v[56:57] op_sel_hi:[1,0]
	v_mul_f32_e32 v58, v63, v63
	v_pk_fma_f32 v[54:55], v[62:63], v[62:63], v[54:55]
	global_load_dwordx4 v[170:173], v32, s[48:49]
	global_load_dwordx4 v[174:177], v32, s[48:49] offset:32
	global_load_dwordx4 v[178:181], v32, s[48:49] offset:64
	global_load_dwordx4 v[182:185], v32, s[48:49] offset:96
	global_load_dwordx4 v[186:189], v32, s[48:49] offset:128
	global_load_dwordx4 v[190:193], v32, s[48:49] offset:160
	global_load_dwordx4 v[202:205], v32, s[48:49] offset:192
	global_load_dwordx4 v[206:209], v32, s[48:49] offset:224
	global_load_dwordx4 v[210:213], v32, s[48:49] offset:256
	global_load_dwordx4 v[214:217], v32, s[48:49] offset:288
	v_pk_fma_f32 v[56:57], v[52:53], v[122:123], v[86:87] op_sel_hi:[0,1,1] neg_lo:[1,0,0] neg_hi:[1,0,0]
	v_pk_add_f32 v[54:55], v[54:55], v[58:59] op_sel_hi:[1,0]
	v_mul_f32_e32 v58, v57, v57
	v_pk_fma_f32 v[54:55], v[56:57], v[56:57], v[54:55]
	v_pk_fma_f32 v[48:49], v[52:53], v[130:131], v[48:49] op_sel_hi:[0,1,1] neg_lo:[1,0,0] neg_hi:[1,0,0]
	v_pk_add_f32 v[86:87], v[54:55], v[58:59] op_sel_hi:[1,0]
	v_pk_fma_f32 v[58:59], v[52:53], v[124:125], v[50:51] op_sel_hi:[0,1,1] neg_lo:[1,0,0] neg_hi:[1,0,0]
	v_pk_fma_f32 v[54:55], v[52:53], v[126:127], v[84:85] op_sel_hi:[0,1,1] neg_lo:[1,0,0] neg_hi:[1,0,0]
; __device__ __forceinline__ float xhalf_sum(float v) { auto rr = __builtin_amdgcn_permlane32_swap(__float_as_uint(v), __float_as_uint(v), false, false); return __uint_as_float(rr[0]) + __uint_as_float(rr[1]); }
; template <int MODE, bool FROZEN = false>
; __device__ __forceinline__ bool attn_unit(LAS unsigned char* lds, const Params& p, int l, int ua, int ub) {
;     ...
;                 for (int r = 0; r < 16; ++r) { const float a = o[nb][r] - lam * ex[(wid * 64 + nb * 16 + r) * 64 + lane]; o[nb][r] = a; ss += a * a; }
;             ss = xhalf_sum(ss);
;             const float rinv = (1.0f - lam_init) / sqrtf(ss * (1.0f / 128.0f) + 1e-6f);
	v_pk_fma_f32 v[50:51], v[58:59], v[58:59], v[86:87]
	v_mul_f32_e32 v84, v59, v59
	v_pk_add_f32 v[50:51], v[50:51], v[84:85] op_sel_hi:[1,0]
	v_mul_f32_e32 v84, v55, v55
	v_pk_fma_f32 v[50:51], v[54:55], v[54:55], v[50:51]
	v_pk_fma_f32 v[44:45], v[52:53], v[134:135], v[44:45] op_sel_hi:[0,1,1] neg_lo:[1,0,0] neg_hi:[1,0,0]
	v_pk_add_f32 v[84:85], v[50:51], v[84:85] op_sel_hi:[1,0]
	v_pk_fma_f32 v[50:51], v[52:53], v[128:129], v[46:47] op_sel_hi:[0,1,1] neg_lo:[1,0,0] neg_hi:[1,0,0]
	v_pk_fma_f32 v[46:47], v[50:51], v[50:51], v[84:85]
	v_mul_f32_e32 v84, v51, v51
	v_pk_add_f32 v[46:47], v[46:47], v[84:85] op_sel_hi:[1,0]
	v_mul_f32_e32 v84, v49, v49
	v_pk_fma_f32 v[46:47], v[48:49], v[48:49], v[46:47]
	v_pk_fma_f32 v[40:41], v[52:53], v[138:139], v[40:41] op_sel_hi:[0,1,1] neg_lo:[1,0,0] neg_hi:[1,0,0]
	v_pk_add_f32 v[84:85], v[46:47], v[84:85] op_sel_hi:[1,0]
	v_pk_fma_f32 v[46:47], v[52:53], v[132:133], v[42:43] op_sel_hi:[0,1,1] neg_lo:[1,0,0] neg_hi:[1,0,0]
	v_pk_fma_f32 v[42:43], v[46:47], v[46:47], v[84:85]
	v_mul_f32_e32 v84, v47, v47
	v_pk_add_f32 v[42:43], v[42:43], v[84:85] op_sel_hi:[1,0]
	v_mul_f32_e32 v84, v45, v45
	v_pk_fma_f32 v[42:43], v[44:45], v[44:45], v[42:43]
	v_pk_fma_f32 v[36:37], v[52:53], v[142:143], v[36:37] op_sel_hi:[0,1,1] neg_lo:[1,0,0] neg_hi:[1,0,0]
	v_pk_add_f32 v[84:85], v[42:43], v[84:85] op_sel_hi:[1,0]
	v_pk_fma_f32 v[42:43], v[52:53], v[136:137], v[38:39] op_sel_hi:[0,1,1] neg_lo:[1,0,0] neg_hi:[1,0,0]
	v_pk_fma_f32 v[38:39], v[42:43], v[42:43], v[84:85]
	v_mul_f32_e32 v84, v43, v43
	v_pk_add_f32 v[38:39], v[38:39], v[84:85] op_sel_hi:[1,0]
	v_mul_f32_e32 v84, v41, v41
	v_pk_fma_f32 v[38:39], v[40:41], v[40:41], v[38:39]
	v_pk_fma_f32 v[28:29], v[52:53], v[144:145], v[28:29] op_sel_hi:[0,1,1] neg_lo:[1,0,0] neg_hi:[1,0,0]
	v_pk_add_f32 v[84:85], v[38:39], v[84:85] op_sel_hi:[1,0]
	v_pk_fma_f32 v[38:39], v[52:53], v[140:141], v[30:31] op_sel_hi:[0,1,1] neg_lo:[1,0,0] neg_hi:[1,0,0]
	v_pk_fma_f32 v[30:31], v[38:39], v[38:39], v[84:85]
	v_mul_f32_e32 v84, v39, v39
	v_pk_add_f32 v[30:31], v[30:31], v[84:85] op_sel_hi:[1,0]
	v_mul_f32_e32 v84, v37, v37
	v_pk_fma_f32 v[30:31], v[36:37], v[36:37], v[30:31]
	v_pk_fma_f32 v[22:23], v[52:53], v[96:97], v[22:23] op_sel_hi:[0,1,1] neg_lo:[1,0,0] neg_hi:[1,0,0]
	v_pk_add_f32 v[84:85], v[30:31], v[84:85] op_sel_hi:[1,0]
	v_pk_fma_f32 v[30:31], v[52:53], v[116:117], v[26:27] op_sel_hi:[0,1,1] neg_lo:[1,0,0] neg_hi:[1,0,0]
	v_pk_fma_f32 v[26:27], v[30:31], v[30:31], v[84:85]
	v_mul_f32_e32 v84, v31, v31
	v_pk_add_f32 v[26:27], v[26:27], v[84:85] op_sel_hi:[1,0]
	v_mul_f32_e32 v84, v29, v29
	v_pk_fma_f32 v[26:27], v[28:29], v[28:29], v[26:27]
	v_pk_fma_f32 v[24:25], v[52:53], v[98:99], v[24:25] op_sel_hi:[0,1,1] neg_lo:[1,0,0] neg_hi:[1,0,0]
	v_pk_add_f32 v[26:27], v[26:27], v[84:85] op_sel_hi:[1,0]
	v_mul_f32_e32 v84, v23, v23
	v_pk_fma_f32 v[26:27], v[22:23], v[22:23], v[26:27]
	v_pk_fma_f32 v[18:19], v[52:53], v[92:93], v[18:19] op_sel_hi:[0,1,1] neg_lo:[1,0,0] neg_hi:[1,0,0]
	v_pk_add_f32 v[26:27], v[26:27], v[84:85] op_sel_hi:[1,0]
	v_mul_f32_e32 v84, v25, v25
	v_pk_fma_f32 v[26:27], v[24:25], v[24:25], v[26:27]
	v_pk_fma_f32 v[20:21], v[52:53], v[94:95], v[20:21] op_sel_hi:[0,1,1] neg_lo:[1,0,0] neg_hi:[1,0,0]
	v_pk_add_f32 v[26:27], v[26:27], v[84:85] op_sel_hi:[1,0]
	v_mul_f32_e32 v84, v19, v19
	v_pk_fma_f32 v[26:27], v[18:19], v[18:19], v[26:27]
	v_pk_fma_f32 v[14:15], v[52:53], v[80:81], v[14:15] op_sel_hi:[0,1,1] neg_lo:[1,0,0] neg_hi:[1,0,0]
	v_pk_add_f32 v[26:27], v[26:27], v[84:85] op_sel_hi:[1,0]
	v_mul_f32_e32 v84, v21, v21
	v_pk_fma_f32 v[26:27], v[20:21], v[20:21], v[26:27]
	v_mul_f32_e32 v80, v15, v15
	v_pk_add_f32 v[26:27], v[26:27], v[84:85] op_sel_hi:[1,0]
	v_pk_fma_f32 v[16:17], v[52:53], v[82:83], v[16:17] op_sel_hi:[0,1,1] neg_lo:[1,0,0] neg_hi:[1,0,0]
	v_pk_fma_f32 v[26:27], v[14:15], v[14:15], v[26:27]
	v_pk_fma_f32 v[10:11], v[52:53], v[74:75], v[10:11] op_sel_hi:[0,1,1] neg_lo:[1,0,0] neg_hi:[1,0,0]
	v_pk_add_f32 v[26:27], v[26:27], v[80:81] op_sel_hi:[1,0]
	v_mul_f32_e32 v80, v17, v17
	v_pk_fma_f32 v[26:27], v[16:17], v[16:17], v[26:27]
	v_mul_f32_e32 v74, v11, v11
	v_pk_add_f32 v[26:27], v[26:27], v[80:81] op_sel_hi:[1,0]
	v_pk_fma_f32 v[12:13], v[52:53], v[78:79], v[12:13] op_sel_hi:[0,1,1] neg_lo:[1,0,0] neg_hi:[1,0,0]
	v_pk_fma_f32 v[26:27], v[10:11], v[10:11], v[26:27]
	v_pk_fma_f32 v[8:9], v[52:53], v[66:67], v[8:9] op_sel_hi:[0,1,1] neg_lo:[1,0,0] neg_hi:[1,0,0]
	v_pk_add_f32 v[26:27], v[26:27], v[74:75] op_sel_hi:[1,0]
	v_mul_f32_e32 v74, v13, v13
	v_pk_fma_f32 v[26:27], v[12:13], v[12:13], v[26:27]
	v_mul_f32_e32 v52, v9, v9
	v_pk_add_f32 v[26:27], v[26:27], v[74:75] op_sel_hi:[1,0]
	s_mov_b32 s0, 0xf800000
	v_pk_fma_f32 v[26:27], v[8:9], v[8:9], v[26:27]
	s_nop 0
	v_pk_add_f32 v[26:27], v[26:27], v[52:53] op_sel_hi:[1,0]
	v_mul_f32_e32 v52, v5, v5
	v_pk_fma_f32 v[26:27], v[4:5], v[4:5], v[26:27]
	s_nop 0
	v_pk_add_f32 v[26:27], v[26:27], v[52:53] op_sel_hi:[1,0]
	s_nop 0
	v_mov_b32_e32 v27, v26
	s_nop 1
	v_permlane32_swap_b32_e32 v26, v27
	v_add_f32_e32 v26, v26, v27
	v_fmamk_f32 v26, v26, 0x3c000000, v229
	v_cmp_gt_f32_e32 vcc, s0, v26
	v_mul_f32_e32 v27, 0x4f800000, v26
	s_nop 0
	v_cndmask_b32_e32 v26, v26, v27, vcc
	v_sqrt_f32_e32 v27, v26
	s_nop 0
	v_add_u32_e32 v52, -1, v27
	v_fma_f32 v53, -v52, v27, v26
	v_cmp_ge_f32_e64 s[0:1], 0, v53
	v_add_u32_e32 v53, 1, v27
	s_nop 0
	v_cndmask_b32_e64 v52, v27, v52, s[0:1]
	v_fma_f32 v27, -v53, v27, v26
	v_cmp_lt_f32_e64 s[0:1], 0, v27
	s_nop 1
	v_cndmask_b32_e64 v27, v52, v53, s[0:1]
	v_mul_f32_e32 v52, 0x37800000, v27
	v_cndmask_b32_e32 v27, v27, v52, vcc
	v_cmp_class_f32_e32 vcc, v26, v230
	s_nop 1
	v_cndmask_b32_e32 v26, v27, v26, vcc
	v_div_scale_f32 v27, s[0:1], v26, v26, v163
	v_rcp_f32_e32 v52, v27
	s_nop 0
	v_fma_f32 v53, -v27, v52, 1.0
	v_fmac_f32_e32 v52, v53, v52
	v_div_scale_f32 v53, vcc, v163, v26, v163
	v_mul_f32_e32 v66, v53, v52
	v_fma_f32 v67, -v27, v66, v53
	v_fmac_f32_e32 v66, v67, v52
	v_fma_f32 v27, -v27, v66, v53
	v_div_fmas_f32 v27, v27, v52, v66
	v_div_fixup_f32 v26, v27, v26, v163
	v_pk_mul_f32 v[52:53], v[68:69], v[26:27] op_sel_hi:[1,0]
	v_pk_mul_f32 v[50:51], v[50:51], v[26:27] op_sel_hi:[1,0]
	s_waitcnt vmcnt(9)
; __device__ __forceinline__ unsigned pk2(float lo, float hi) { return pg8::cvt_pk_bf16(lo, hi); }
; template <int MODE, bool FROZEN = false>
; __device__ __forceinline__ bool attn_unit(LAS unsigned char* lds, const Params& p, int l, int ua, int ub) {
;     ...
; #pragma unroll
;             for (int nb = 0; nb < NB; ++nb)
; #pragma unroll
;                 for (int rq = 0; rq < 4; ++rq) {
;                     const int dv = 32 * nb + 8 * rq + 4 * hi; const f32x4 gg = *(const f32x4*)(sg + dv);
;                     u32x2 w; w.x = pk2(o[nb][4 * rq] * rinv * gg.x, o[nb][4 * rq + 1] * rinv * gg.y); w.y = pk2(o[nb][4 * rq + 2] * rinv * gg.z, o[nb][4 * rq + 3] * rinv * gg.w);
;                     *(u32x2*)(op + dv) = w;
;                 }
	v_pk_mul_f32 v[170:171], v[170:171], v[52:53]
	v_pk_mul_f32 v[52:53], v[64:65], v[26:27] op_sel_hi:[1,0]
	v_cvt_pk_bf16_f32 v170, v170, v171
	v_pk_mul_f32 v[172:173], v[172:173], v[52:53]
	v_pk_mul_f32 v[52:53], v[88:89], v[26:27] op_sel_hi:[1,0]
	v_cvt_pk_bf16_f32 v171, v172, v173
	global_store_dwordx2 v[6:7], v[170:171], off
	s_nop 0
	global_load_dwordx4 v[170:173], v32, s[48:49] offset:320
	v_pk_mul_f32 v[48:49], v[48:49], v[26:27] op_sel_hi:[1,0]
	v_pk_mul_f32 v[46:47], v[46:47], v[26:27] op_sel_hi:[1,0]
	v_pk_mul_f32 v[44:45], v[44:45], v[26:27] op_sel_hi:[1,0]
	v_pk_mul_f32 v[42:43], v[42:43], v[26:27] op_sel_hi:[1,0]
	v_pk_mul_f32 v[40:41], v[40:41], v[26:27] op_sel_hi:[1,0]
	v_pk_mul_f32 v[38:39], v[38:39], v[26:27] op_sel_hi:[1,0]
	v_pk_mul_f32 v[36:37], v[36:37], v[26:27] op_sel_hi:[1,0]
	v_pk_mul_f32 v[30:31], v[30:31], v[26:27] op_sel_hi:[1,0]
	v_pk_mul_f32 v[28:29], v[28:29], v[26:27] op_sel_hi:[1,0]
	v_pk_mul_f32 v[22:23], v[22:23], v[26:27] op_sel_hi:[1,0]
	v_pk_mul_f32 v[18:19], v[18:19], v[26:27] op_sel_hi:[1,0]
	v_pk_mul_f32 v[14:15], v[14:15], v[26:27] op_sel_hi:[1,0]
	v_pk_mul_f32 v[10:11], v[10:11], v[26:27] op_sel_hi:[1,0]
	v_pk_mul_f32 v[8:9], v[8:9], v[26:27] op_sel_hi:[1,0]
	v_pk_mul_f32 v[4:5], v[4:5], v[26:27] op_sel_hi:[1,0]
	s_waitcnt vmcnt(10)
	v_pk_mul_f32 v[174:175], v[174:175], v[52:53]
	v_pk_mul_f32 v[52:53], v[76:77], v[26:27] op_sel_hi:[1,0]
	v_cvt_pk_bf16_f32 v174, v174, v175
	v_pk_mul_f32 v[176:177], v[176:177], v[52:53]
	v_pk_mul_f32 v[52:53], v[90:91], v[26:27] op_sel_hi:[1,0]
	v_cvt_pk_bf16_f32 v175, v176, v177
	global_store_dwordx2 v[6:7], v[174:175], off offset:16
	s_nop 0
	global_load_dwordx4 v[174:177], v32, s[48:49] offset:352
	s_waitcnt vmcnt(11)
	v_pk_mul_f32 v[178:179], v[178:179], v[52:53]
	v_pk_mul_f32 v[52:53], v[70:71], v[26:27] op_sel_hi:[1,0]
	v_cvt_pk_bf16_f32 v178, v178, v179
	v_pk_mul_f32 v[180:181], v[180:181], v[52:53]
	v_pk_mul_f32 v[52:53], v[72:73], v[26:27] op_sel_hi:[1,0]
	v_cvt_pk_bf16_f32 v179, v180, v181
	global_store_dwordx2 v[6:7], v[178:179], off offset:32
	s_nop 0
	global_load_dwordx4 v[178:181], v32, s[48:49] offset:384
	s_waitcnt vmcnt(12)
	v_pk_mul_f32 v[182:183], v[52:53], v[182:183]
	v_pk_mul_f32 v[52:53], v[60:61], v[26:27] op_sel_hi:[1,0]
	v_cvt_pk_bf16_f32 v182, v182, v183
	v_pk_mul_f32 v[184:185], v[52:53], v[184:185]
	v_pk_mul_f32 v[52:53], v[62:63], v[26:27] op_sel_hi:[1,0]
	v_cvt_pk_bf16_f32 v183, v184, v185
	global_store_dwordx2 v[6:7], v[182:183], off offset:48
	s_nop 0
	global_load_dwordx4 v[182:185], v32, s[48:49] offset:416
	s_waitcnt vmcnt(13)
	v_pk_mul_f32 v[186:187], v[52:53], v[186:187]
	v_pk_mul_f32 v[52:53], v[56:57], v[26:27] op_sel_hi:[1,0]
	v_cvt_pk_bf16_f32 v186, v186, v187
	v_pk_mul_f32 v[188:189], v[52:53], v[188:189]
	v_pk_mul_f32 v[52:53], v[58:59], v[26:27] op_sel_hi:[1,0]
	v_cvt_pk_bf16_f32 v187, v188, v189
	global_store_dwordx2 v[6:7], v[186:187], off offset:64
	s_nop 0
	global_load_dwordx4 v[186:189], v32, s[48:49] offset:448
	s_waitcnt vmcnt(14)
	v_pk_mul_f32 v[190:191], v[52:53], v[190:191]
	v_pk_mul_f32 v[52:53], v[54:55], v[26:27] op_sel_hi:[1,0]
	v_cvt_pk_bf16_f32 v190, v190, v191
	v_pk_mul_f32 v[192:193], v[52:53], v[192:193]
	s_nop 0
	v_cvt_pk_bf16_f32 v191, v192, v193
	global_store_dwordx2 v[6:7], v[190:191], off offset:80
	s_nop 0
	global_load_dwordx4 v[190:193], v32, s[48:49] offset:480
	s_waitcnt vmcnt(15)
	v_pk_mul_f32 v[202:203], v[50:51], v[202:203]
	v_pk_mul_f32 v[204:205], v[48:49], v[204:205]
	v_cvt_pk_bf16_f32 v202, v202, v203
	v_cvt_pk_bf16_f32 v203, v204, v205
	global_store_dwordx2 v[6:7], v[202:203], off offset:96
	s_waitcnt vmcnt(15)
	v_pk_mul_f32 v[206:207], v[46:47], v[206:207]
	v_pk_mul_f32 v[208:209], v[44:45], v[208:209]
	v_cvt_pk_bf16_f32 v206, v206, v207
	v_cvt_pk_bf16_f32 v207, v208, v209
	global_store_dwordx2 v[6:7], v[206:207], off offset:112
	s_waitcnt vmcnt(15)
	v_pk_mul_f32 v[210:211], v[42:43], v[210:211]
	v_pk_mul_f32 v[212:213], v[40:41], v[212:213]
	v_cvt_pk_bf16_f32 v210, v210, v211
	v_cvt_pk_bf16_f32 v211, v212, v213
	global_store_dwordx2 v[6:7], v[210:211], off offset:128
	s_waitcnt vmcnt(15)
	v_pk_mul_f32 v[214:215], v[38:39], v[214:215]
	v_pk_mul_f32 v[216:217], v[36:37], v[216:217]
	v_cvt_pk_bf16_f32 v214, v214, v215
	v_cvt_pk_bf16_f32 v215, v216, v217
	global_store_dwordx2 v[6:7], v[214:215], off offset:144
	s_waitcnt vmcnt(14)
	v_pk_mul_f32 v[170:171], v[30:31], v[170:171]
	v_pk_mul_f32 v[172:173], v[28:29], v[172:173]
	v_cvt_pk_bf16_f32 v170, v170, v171
	v_cvt_pk_bf16_f32 v171, v172, v173
	global_store_dwordx2 v[6:7], v[170:171], off offset:160
	s_waitcnt vmcnt(13)
	v_pk_mul_f32 v[174:175], v[22:23], v[174:175]
	v_pk_mul_f32 v[22:23], v[24:25], v[26:27] op_sel_hi:[1,0]
	v_cvt_pk_bf16_f32 v174, v174, v175
	v_pk_mul_f32 v[176:177], v[22:23], v[176:177]
	s_nop 0
	v_cvt_pk_bf16_f32 v175, v176, v177
	global_store_dwordx2 v[6:7], v[174:175], off offset:176
	s_waitcnt vmcnt(12)
	v_pk_mul_f32 v[178:179], v[18:19], v[178:179]
	v_pk_mul_f32 v[18:19], v[20:21], v[26:27] op_sel_hi:[1,0]
	v_cvt_pk_bf16_f32 v178, v178, v179
	v_pk_mul_f32 v[180:181], v[18:19], v[180:181]
	s_nop 0
	v_cvt_pk_bf16_f32 v179, v180, v181
	global_store_dwordx2 v[6:7], v[178:179], off offset:192
	s_waitcnt vmcnt(11)
	v_pk_mul_f32 v[182:183], v[14:15], v[182:183]
	v_pk_mul_f32 v[14:15], v[16:17], v[26:27] op_sel_hi:[1,0]
	v_cvt_pk_bf16_f32 v182, v182, v183
	v_pk_mul_f32 v[184:185], v[14:15], v[184:185]
	s_nop 0
	v_cvt_pk_bf16_f32 v183, v184, v185
	global_store_dwordx2 v[6:7], v[182:183], off offset:208
	s_waitcnt vmcnt(10)
	v_pk_mul_f32 v[186:187], v[10:11], v[186:187]
	v_pk_mul_f32 v[10:11], v[12:13], v[26:27] op_sel_hi:[1,0]
	v_cvt_pk_bf16_f32 v186, v186, v187
	v_pk_mul_f32 v[188:189], v[10:11], v[188:189]
	s_nop 0
	v_cvt_pk_bf16_f32 v187, v188, v189
	global_store_dwordx2 v[6:7], v[186:187], off offset:224
	s_waitcnt vmcnt(9)
	v_pk_mul_f32 v[190:191], v[8:9], v[190:191]
	v_pk_mul_f32 v[192:193], v[4:5], v[192:193]
	v_cvt_pk_bf16_f32 v190, v190, v191
	v_cvt_pk_bf16_f32 v191, v192, v193
	global_store_dwordx2 v[6:7], v[190:191], off offset:240
	s_branch .LBB0_92
